# mixer dynamic queue: prefetch next unit index (atomic issued one unit ahead, landed in v201)
# baseline (speedup 1.0000x reference)
; __device__ __forceinline__ int opaque_tid() { int t = threadIdx.x; asm volatile("" : "+v"(t)); return t; }
; __device__ __forceinline__ void mixer_phase(const Args& a, LAS unsigned char* lds, int l, unsigned* ctr) {
;     ...
;     for (;;) {
;         if (opaque_tid() == 0) *sidx = atomicAdd(ctr, 1u);
;         __syncthreads();
;         const int idx = (int)*sidx;
.Lmix_prio_skip:
	v_cmp_eq_u32_e32 vcc, 0, v192
	s_and_saveexec_b64 s[0:1], vcc
	s_cbranch_execz .Lmix_q_pre
	global_atomic_add v201, v195, v206, s[78:79] sc0
.Lmix_q_pre:
	s_or_b64 exec, exec, s[0:1]
	s_branch .LBB0_581

; __device__ __forceinline__ int opaque_tid() { int t = threadIdx.x; asm volatile("" : "+v"(t)); return t; }
; __device__ __forceinline__ void mixer_phase(const Args& a, LAS unsigned char* lds, int l, unsigned* ctr) {
;     ...
;     for (;;) {
;         if (opaque_tid() == 0) *sidx = atomicAdd(ctr, 1u);
;         __syncthreads();
;         const int idx = (int)*sidx;
;         __syncthreads();
;         if (idx >= total) break;
.LBB0_581:
	v_mov_b32_e32 v0, v192
	s_nop 0
	v_cmp_eq_u32_e32 vcc, 0, v0
	s_and_saveexec_b64 s[0:1], vcc
	s_cbranch_execz .LBB0_585
	s_waitcnt vmcnt(0)
	v_mov_b32_e32 v0, v201
	v_mov_b32_e32 v1, s75
	s_nop 0
	ds_write_b32 v1, v0
	global_atomic_add v201, v195, v206, s[78:79] sc0

.LBB0_654:
	v_add_u32_e32 v200, s10, v223
	v_mov_b32_e32 v96, 0
	v_mov_b32_e32 v124, 0
	v_add_u32_e32 v97, v200, v96
	ds_read_b128 v[114:117], v97
	ds_read_b128 v[132:135], v97 offset:512
	v_add_u32_e32 v96, v221, v96
	ds_read_b128 v[128:131], v96 offset:51200
	v_exp_f32_e32 v125, v176
	v_add_u32_e32 v118, v200, v124
	ds_read_b128 v[136:139], v118 offset:2048
	s_waitcnt lgkmcnt(0)
	v_mfma_f32_32x32x16_bf16 v[96:111], v[114:117], v[128:131], v[144:159]
	ds_read_b128 v[116:119], v118 offset:2560
	v_add_u32_e32 v114, v221, v124
	v_exp_f32_e32 v124, v178
	v_add_f32_e32 v140, v121, v120
	v_add_f32_e32 v141, v123, v122
	v_exp_f32_e32 v229, v166
	v_exp_f32_e32 v211, v167
	v_mfma_f32_32x32x16_bf16 v[144:159], v[132:135], v[128:131], v[144:159]
	v_exp_f32_e32 v133, v177
	v_exp_f32_e32 v129, v160
	v_exp_f32_e32 v131, v161
	v_exp_f32_e32 v132, v179
	v_exp_f32_e32 v128, v162
	v_exp_f32_e32 v130, v163
	ds_read_b128 v[120:123], v114 offset:59392
	v_add_f32_e32 v134, v132, v124
	v_add_f32_e32 v135, v133, v125
	s_waitcnt lgkmcnt(0)
	v_mfma_f32_32x32x16_bf16 v[96:111], v[136:139], v[120:123], v[96:111]
	v_add_f32_e64 v142, v130, v128
	v_add_f32_e64 v143, v131, v129
	v_mov_b32_e32 v136, 0
	v_add_f32_e64 v134, v142, v134
	v_add_f32_e64 v135, v143, v135
	v_cvt_pk_bf16_f32 v114, v125, v133
	v_add_f32_e32 v115, 0, v135
	v_add_f32_e32 v143, v134, v115
	v_cvt_pk_bf16_f32 v115, v124, v132
	v_exp_f32_e32 v133, v180
	v_add_u32_e32 v124, v200, v136
	v_exp_f32_e32 v135, v181
	v_exp_f32_e32 v132, v164
	v_exp_f32_e32 v134, v165
	ds_read_b128 v[160:163], v124 offset:4096
	v_mfma_f32_32x32x16_bf16 v[144:159], v[116:119], v[120:123], v[144:159]
	ds_read_b128 v[122:125], v124 offset:4608
	v_add3_u32 v116, v221, v136, s45
	ds_read_b128 v[176:179], v116
	v_add_f32_e64 v116, v134, v132
	v_add_f32_e64 v117, v135, v133
	v_exp_f32_e32 v118, v182
	v_exp_f32_e32 v119, v183
	v_add_f32_e32 v166, v116, v116
	v_add_f32_e32 v167, v116, v117
	v_exp_f32_e32 v142, v184
	v_exp_f32_e32 v166, v185
	v_exp_f32_e32 v136, v168
	v_exp_f32_e32 v138, v169
	v_mov_b32_e32 v224, 0
	v_exp_f32_e32 v181, v186
	v_exp_f32_e32 v183, v187
	v_exp_f32_e32 v180, v170
	v_exp_f32_e32 v182, v171
	v_cvt_pk_bf16_f32 v116, v133, v135
	v_add_f32_e32 v137, v119, v118
	v_add_f32_e32 v139, v211, v229
	v_cvt_pk_bf16_f32 v117, v118, v119
	v_add_u32_e32 v133, v200, v224
	s_waitcnt lgkmcnt(0)
	v_mfma_f32_32x32x16_bf16 v[96:111], v[160:163], v[176:179], v[96:111]
	ds_read_b128 v[118:121], v133 offset:6144
	v_add_f32_e64 v160, v166, v142
	v_add_f32_e64 v161, v167, v143
	v_add_f32_e64 v162, v138, v136
	v_add_f32_e64 v163, v139, v137
	v_exp_f32_e32 v185, v188
	v_add_f32_e32 v160, v162, v160
	v_add_f32_e32 v161, v163, v161
	v_exp_f32_e32 v187, v189
	v_add_f32_e32 v164, v160, v160
	v_add_f32_e32 v165, v160, v161
	v_mfma_f32_32x32x16_bf16 v[144:159], v[122:125], v[176:179], v[144:159]
	ds_read_b128 v[122:125], v133 offset:6656
	ds_read_b128 v[168:171], v63 offset:8704
	v_cvt_pk_bf16_f32 v160, v142, v166
	v_add_f32_e64 v142, v182, v180
	v_add_f32_e64 v143, v183, v181
	v_exp_f32_e32 v164, v190
	v_add_f32_e32 v166, v142, v142
	v_add_f32_e32 v167, v142, v143
	v_exp_f32_e32 v166, v191
	s_waitcnt lgkmcnt(0)
	v_mfma_f32_32x32x16_bf16 v[32:47], v[114:117], v[168:171], v[32:47]
	ds_read_b128 v[176:179], v63 offset:10752
	v_cvt_pk_bf16_f32 v161, v181, v183
	v_cvt_pk_bf16_f32 v162, v185, v187
	v_cvt_pk_bf16_f32 v163, v164, v166
	v_cvt_pk_bf16_f32 v168, v129, v131
	v_cvt_pk_bf16_f32 v169, v128, v130
	v_cvt_pk_bf16_f32 v170, v132, v134
	s_waitcnt lgkmcnt(0)
	v_mfma_f32_32x32x16_bf16 v[32:47], v[160:163], v[176:179], v[32:47]
	ds_read_b128 v[128:131], v63 offset:12800
	v_cvt_pk_bf16_f32 v171, v229, v211
	v_exp_f32_e32 v181, v172
	v_exp_f32_e32 v183, v173
	v_exp_f32_e32 v184, v174
	v_exp_f32_e32 v186, v175
	v_cvt_pk_bf16_f32 v176, v136, v138
	s_waitcnt lgkmcnt(0)
	v_mfma_f32_32x32x16_bf16 v[32:47], v[168:171], v[128:131], v[32:47]
	ds_read_b128 v[132:135], v63 offset:14848
	v_cvt_pk_bf16_f32 v177, v180, v182
	v_cvt_pk_bf16_f32 v178, v181, v183
	v_cvt_pk_bf16_f32 v179, v184, v186
	v_add_f32_e32 v129, v234, v215
	v_add_f32_e32 v130, v237, v235
	v_add_f32_e32 v129, v130, v129
	v_add3_u32 v130, v221, v224, s18
	s_waitcnt lgkmcnt(0)
	v_mfma_f32_32x32x16_bf16 v[32:47], v[176:179], v[132:135], v[32:47]
	ds_read_b128 v[172:175], v130
	v_add_f32_e32 v128, v141, v140
	v_add_f32_e32 v128, 0, v128
	v_add_f32_e32 v128, v129, v128
	v_add_f32_e32 v113, v213, v113
	v_add_f32_e32 v129, v236, v232
	v_add_f32_e32 v113, v129, v113
	s_waitcnt lgkmcnt(0)
	v_mfma_f32_32x32x16_bf16 v[96:111], v[118:121], v[172:175], v[96:111]
	v_add_f32_e32 v118, v238, v233
	v_add_f32_e32 v119, v240, v239
	v_add_f32_e32 v113, v113, v128
	v_add_f32_e32 v118, v119, v118
	v_add_f32_e32 v113, v118, v113
	ds_read_b128 v[118:121], v63 offset:8192
	v_mov_b64_e32 v[128:129], v[144:145]
	v_mov_b64_e32 v[130:131], v[146:147]
	v_mov_b64_e32 v[132:133], v[148:149]
	v_mov_b64_e32 v[134:135], v[150:151]
	v_mov_b64_e32 v[136:137], v[152:153]
	v_mov_b64_e32 v[138:139], v[154:155]
	v_mov_b64_e32 v[140:141], v[156:157]
	v_mov_b64_e32 v[142:143], v[158:159]
	v_add_f32_e32 v144, v250, v249
	v_add_f32_e32 v145, v228, v227
	v_mfma_f32_32x32x16_bf16 v[128:143], v[122:125], v[172:175], v[128:143]
	v_add_f32_e32 v122, v242, v241
	v_add_f32_e32 v123, v247, v245
	v_add_f32_e32 v122, v123, v122
	v_add_f32_e32 v113, v122, v113
	ds_read_b128 v[122:125], v63 offset:10240
	v_add_f32_e32 v185, v187, v185
	v_add_f32_e32 v187, v183, v181
	s_waitcnt lgkmcnt(0)
	v_mfma_f32_32x32x16_bf16 v[64:79], v[114:117], v[118:121], v[64:79]
	v_add_f32_e32 v114, v145, v144
	v_add_f32_e32 v113, v114, v113
	v_add_f32_e32 v114, v248, v246
	v_add_f32_e32 v115, v226, v225
	v_add_f32_e32 v114, v115, v114
	v_add_f32_e32 v113, v114, v113
	ds_read_b128 v[114:117], v63 offset:12288
	v_mfma_f32_32x32x16_bf16 v[64:79], v[160:163], v[122:125], v[64:79]
	v_add_f32_e32 v118, v244, v243
	v_add_f32_e32 v119, v230, v251
	v_add_f32_e32 v118, v119, v118
	v_add_f32_e32 v113, v118, v113
	ds_read_b128 v[118:121], v63 offset:14336
	s_waitcnt vmcnt(0)
	s_add_i32 s9, s9, 1
	s_waitcnt lgkmcnt(0)
	v_mfma_f32_32x32x16_bf16 v[64:79], v[168:171], v[114:117], v[64:79]
	v_add_f32_e64 v114, v166, v164
	v_add_f32_e64 v115, v167, v165
	v_add_f32_e64 v116, v186, v184
	v_add_f32_e64 v117, v187, v185
	v_add_f32_e32 v209, v209, v113
	v_add_f32_e32 v114, v116, v114
	v_add_f32_e32 v115, v117, v115
	v_add_u32_e32 v212, 0x1000, v212
	v_pk_add_f32 v[114:115], v[114:115], v[114:115] op_sel:[0,1] op_sel_hi:[1,0]
	s_cmpk_eq_i32 s9, 0x83
	v_mfma_f32_32x32x16_bf16 v[64:79], v[176:179], v[118:121], v[64:79]
	v_add_f32_e64 v114, v127, v114
	v_add_f32_e64 v115, v126, v115
	v_add_u32_e32 v214, 64, v214
	s_waitcnt vmcnt(0)
	s_barrier
	s_cbranch_scc1 .LBB0_844
	s_mov_b32 s6, s10
	s_mov_b32 s10, s5
	s_mov_b32 s5, s11
	v_mov_b32_e32 v211, v114
	s_cmpk_gt_u32 s9, 0x80
	s_mov_b32 s11, s6
	s_cbranch_scc0 .LBB0_640
	s_branch .LBB0_644
